# fast path v8: row-sum chains in the PV gaps as scalar v_add_f32 pairs instead of v_pk_add_f32
# speedup vs baseline: 1.0238x; 1.0049x over previous
; DI void attn_item(const Params& p, int g, int seq, int hd, int qt, int m, char* smem, int split_j, int sub) {
;     ...
;   auto compute = [&](int st, int buf) __attribute__((always_inline)) {
;     const int k0 = (tbase + st) * 32, h = h_, l31 = l31_;
;     const bf16_t* Kb = Ks + buf * 32 * 72; const bf16_t* Vb = Vs + buf * 128 * 40;
;     const int rmin = k0 - (qw0 + 31), rmax = k0 + 31 - qw0;
;     const bool farL = rmax <= -128, farR = rmin >= 128;
;     if (!farL && region == 0) { rescale(__builtin_amdgcn_exp2f(cneg)); region = 1; }
;     if (farR && region == 1) { rescale(__builtin_amdgcn_exp2f(-cpos)); region = 2; }
;     bf16x8 kf[4], vf[2][4];
; #pragma unroll
;     for (int s = 0; s < 4; ++s) kf[s] = *(const bf16x8*)(Kb + l31 * 72 + s * 16 + h * 8);
; #pragma unroll
;     for (int s2 = 0; s2 < 2; ++s2)
; #pragma unroll
;       for (int dt = 0; dt < 4; ++dt) vf[s2][dt] = *(const bf16x8*)(Vb + (dt * 32 + l31) * 40 + s2 * 16 + h * 8);
;     __builtin_amdgcn_sched_barrier(0);
;     f32x16 X;
; #pragma unroll
;     for (int r = 0; r < 16; ++r) X[r] = 0.f;
; #pragma unroll
;     for (int s = 0; s < 4; ++s) X = MFMA32(kf[s], qf[s], X);
;     if (farL || farR) {
; #pragma unroll
;       for (int r = 0; r < 16; ++r) X[r] = __builtin_amdgcn_exp2f(X[r]);
;     } else {
;       const int rel0 = k0 - (qw0 + l31) + 128;
; #pragma unroll
;       for (int r = 0; r < 16; ++r) { int idx = rel0 + crow(r, h); idx = idx < 0 ? 0 : (idx > 256 ? 256 : idx); X[r] = __builtin_amdgcn_exp2f(X[r] + tab[idx]); }
;     }
;     bf16x8 pf[2];
; #pragma unroll
;     for (int s2 = 0; s2 < 2; ++s2) {
;       u32x4 w; w.x = pk_bf16(X[8 * s2], X[8 * s2 + 1]); w.y = pk_bf16(X[8 * s2 + 2], X[8 * s2 + 3]); w.z = pk_bf16(X[8 * s2 + 4], X[8 * s2 + 5]); w.w = pk_bf16(X[8 * s2 + 6], X[8 * s2 + 7]);
;       ls2 += (f32x2){X[8 * s2], X[8 * s2 + 1]}; ls2 += (f32x2){X[8 * s2 + 2], X[8 * s2 + 3]};
;       ls2 += (f32x2){X[8 * s2 + 4], X[8 * s2 + 5]}; ls2 += (f32x2){X[8 * s2 + 6], X[8 * s2 + 7]};
;       pf[s2] = __builtin_bit_cast(bf16x8, w);
;     }
; #pragma unroll
;     for (int s2 = 0; s2 < 2; ++s2)
; #pragma unroll
;       for (int dt = 0; dt < 4; ++dt) O[dt] = MFMA32(pf[s2], vf[s2][dt], O[dt]);
;   };
;   load_tile(0, rkA, rvA0, rvA1);
;   load_tile(1, rkB, rvB0, rvB1);
;   __syncthreads();
;   store_tile(0, rkA, rvA0, rvA1);
;   store_tile(1, rkB, rvB0, rvB1);
;   __syncthreads();
.Lat2_reads:
	ds_read_b128 v[64:67], v192
	ds_read_b128 v[80:83], v192 offset:32
	ds_read_b128 v[84:87], v192 offset:64
	ds_read_b128 v[88:91], v192 offset:96
	ds_read_b128 v[220:223], v192 offset:4608
	ds_read_b128 v[224:227], v192 offset:4640
	ds_read_b128 v[236:239], v192 offset:4672
	ds_read_b128 v[240:243], v192 offset:4704
	ds_read_b128 v[156:159], v244 offset:18432
	ds_read_b128 v[160:163], v244 offset:20992
	ds_read_b128 v[164:167], v244 offset:23552
	ds_read_b128 v[152:155], v244 offset:26112
	s_waitcnt lgkmcnt(11)
	v_mfma_f32_32x32x16_bf16 v[64:79], v[64:67], v[104:107], 0
	s_waitcnt lgkmcnt(10)
	v_mfma_f32_32x32x16_bf16 v[64:79], v[80:83], v[108:111], v[64:79]
	s_waitcnt lgkmcnt(9)
	v_mfma_f32_32x32x16_bf16 v[64:79], v[84:87], v[112:115], v[64:79]
	s_waitcnt lgkmcnt(8)
	v_mfma_f32_32x32x16_bf16 v[64:79], v[88:91], v[116:119], v[64:79]
	ds_read_b128 v[148:151], v244 offset:18464
	ds_read_b128 v[144:147], v244 offset:21024
	ds_read_b128 v[136:139], v244 offset:23584
	ds_read_b128 v[140:143], v244 offset:26144
	s_waitcnt lgkmcnt(11)
	v_mfma_f32_32x32x16_bf16 v[80:95], v[220:223], v[104:107], 0
	s_waitcnt lgkmcnt(10)
	v_mfma_f32_32x32x16_bf16 v[80:95], v[224:227], v[108:111], v[80:95]
	v_exp_f32_e32 v64, v64
	v_exp_f32_e32 v65, v65
	v_exp_f32_e32 v66, v66
	v_exp_f32_e32 v67, v67
	v_exp_f32_e32 v68, v68
	v_exp_f32_e32 v69, v69
	s_waitcnt lgkmcnt(9)
	v_mfma_f32_32x32x16_bf16 v[80:95], v[236:239], v[112:115], v[80:95]
	v_exp_f32_e32 v70, v70
	v_exp_f32_e32 v71, v71
	v_exp_f32_e32 v72, v72
	v_exp_f32_e32 v73, v73
	v_exp_f32_e32 v74, v74
	v_exp_f32_e32 v75, v75
	s_waitcnt lgkmcnt(8)
	v_mfma_f32_32x32x16_bf16 v[80:95], v[240:243], v[116:119], v[80:95]
	v_exp_f32_e32 v76, v76
	v_exp_f32_e32 v77, v77
	v_exp_f32_e32 v78, v78
	v_exp_f32_e32 v79, v79
	v_cvt_pk_bf16_f32 v220, v64, v65
	v_cvt_pk_bf16_f32 v221, v66, v67
	v_cvt_pk_bf16_f32 v222, v68, v69
	v_cvt_pk_bf16_f32 v223, v70, v71
	v_cvt_pk_bf16_f32 v224, v72, v73
	v_cvt_pk_bf16_f32 v225, v74, v75
	v_cvt_pk_bf16_f32 v226, v76, v77
	v_cvt_pk_bf16_f32 v227, v78, v79
	s_waitcnt lgkmcnt(7)
	v_mfma_f32_32x32x16_bf16 v[48:63], v[220:223], v[156:159], v[48:63]
	ds_read_b128 v[156:159], v244 offset:28672
	v_exp_f32_e32 v80, v80
	v_exp_f32_e32 v81, v81
	v_exp_f32_e32 v82, v82
	s_waitcnt lgkmcnt(7)
	v_mfma_f32_32x32x16_bf16 v[32:47], v[220:223], v[160:163], v[32:47]
	ds_read_b128 v[160:163], v244 offset:31232
	v_exp_f32_e32 v83, v83
	v_exp_f32_e32 v84, v84
	v_exp_f32_e32 v85, v85
	s_waitcnt lgkmcnt(7)
	v_mfma_f32_32x32x16_bf16 v[16:31], v[220:223], v[164:167], v[16:31]
	ds_read_b128 v[164:167], v244 offset:33792
	v_exp_f32_e32 v86, v86
	v_exp_f32_e32 v87, v87
	v_exp_f32_e32 v88, v88
	s_waitcnt lgkmcnt(7)
	v_mfma_f32_32x32x16_bf16 v[0:15], v[220:223], v[152:155], v[0:15]
	ds_read_b128 v[152:155], v244 offset:36352
	v_exp_f32_e32 v89, v89
	v_exp_f32_e32 v90, v90
	v_exp_f32_e32 v91, v91
	s_waitcnt lgkmcnt(7)
	v_mfma_f32_32x32x16_bf16 v[48:63], v[224:227], v[148:151], v[48:63]
	ds_read_b128 v[148:151], v244 offset:28704
	v_exp_f32_e32 v92, v92
	v_exp_f32_e32 v93, v93
	v_exp_f32_e32 v94, v94
	v_exp_f32_e32 v95, v95
	s_waitcnt lgkmcnt(7)
	v_mfma_f32_32x32x16_bf16 v[32:47], v[224:227], v[144:147], v[32:47]
	ds_read_b128 v[144:147], v244 offset:31264
	v_cvt_pk_bf16_f32 v236, v80, v81
	v_cvt_pk_bf16_f32 v237, v82, v83
	v_cvt_pk_bf16_f32 v238, v84, v85
	s_waitcnt lgkmcnt(7)
	v_mfma_f32_32x32x16_bf16 v[16:31], v[224:227], v[136:139], v[16:31]
	ds_read_b128 v[136:139], v244 offset:33824
	v_cvt_pk_bf16_f32 v239, v86, v87
	v_cvt_pk_bf16_f32 v240, v88, v89
	v_cvt_pk_bf16_f32 v241, v90, v91
	s_waitcnt lgkmcnt(7)
	v_mfma_f32_32x32x16_bf16 v[0:15], v[224:227], v[140:143], v[0:15]
	ds_read_b128 v[140:143], v244 offset:36384
	v_cvt_pk_bf16_f32 v242, v92, v93
	v_cvt_pk_bf16_f32 v243, v94, v95
	s_andn2_b64 vcc, exec, s[8:9]
	s_cbranch_vccnz .Lat2_pvplain
	s_add_i32 s10, s15, 1
	s_cmp_lt_u32 s10, s73
	s_cbranch_scc0 .Lat2_pvw
	s_xor_b32 s7, s16, 2
	s_mul_i32 s8, s7, 0x2800
	s_add_i32 s8, s8, 32
	s_mulk_i32 s7, 0x1200
	v_add_u32_e32 v192, s7, v169
	v_add3_u32 v244, s8, v189, v190
	s_addk_i32 s8, 0x2800
	s_add_i32 s13, s13, 64
	s_add_i32 s6, s6, 2
	s_mov_b32 s15, s10
	s_mov_b64 s[20:21], 0x1000
	s_waitcnt lgkmcnt(7)
	v_mfma_f32_32x32x16_bf16 v[48:63], v[236:239], v[156:159], v[48:63]
	s_waitcnt vmcnt(5)
	ds_write_b128 v192, v[96:99]
	s_add_i32 s50, s6, -1
	s_lshl_b64 s[10:11], s[50:51], 12
	v_lshl_add_u64 v[220:221], v[172:173], 0, s[10:11]
	v_add_f32_e32 v246, v66, v70
	v_add_f32_e32 v247, v67, v71
	v_add_f32_e32 v186, v186, v64
	v_add_f32_e32 v187, v187, v65
	s_waitcnt lgkmcnt(7)
	v_mfma_f32_32x32x16_bf16 v[32:47], v[236:239], v[160:163], v[32:47]
	s_waitcnt vmcnt(4)
	ds_write_b128 v244, v[100:103] offset:18432
	global_load_dwordx4 v[96:99], v[220:221], off
	s_lshl_b64 s[10:11], s[50:51], 13
	v_lshl_add_u64 v[222:223], v[170:171], 0, s[10:11]
	v_add_f32_e32 v246, v246, v74
	v_add_f32_e32 v247, v247, v75
	v_add_f32_e32 v186, v186, v68
	v_add_f32_e32 v187, v187, v69
	s_waitcnt lgkmcnt(7)
	v_mfma_f32_32x32x16_bf16 v[16:31], v[236:239], v[164:167], v[16:31]
	s_waitcnt vmcnt(4)
	ds_write_b128 v244, v[120:123] offset:23552
	global_load_dwordx4 v[100:103], v[222:223], off
	v_lshl_add_u64 v[224:225], v[222:223], 0, s[20:21]
	v_add_f32_e32 v246, v246, v78
	v_add_f32_e32 v247, v247, v79
	v_add_f32_e32 v186, v186, v72
	v_add_f32_e32 v187, v187, v73
	s_waitcnt lgkmcnt(7)
	v_mfma_f32_32x32x16_bf16 v[0:15], v[236:239], v[152:155], v[0:15]
	s_waitcnt vmcnt(4)
; #define MFMA32(a, b, c) __builtin_amdgcn_mfma_f32_32x32x16_bf16((a), (b), (c), 0, 0, 0)
; DI unsigned pk_bf16(float lo, float hi) { f32x2 v = {lo, hi}; bf16v2 b = __builtin_convertvector(v, bf16v2); return __builtin_bit_cast(unsigned, b); }
; DI void attn_item(const Params& p, int g, int seq, int hd, int qt, int m, char* smem, int split_j, int sub) {
;     ...
;     bf16x8 pf[2];
; #pragma unroll
;     for (int s2 = 0; s2 < 2; ++s2) {
;       u32x4 w; w.x = pk_bf16(X[8 * s2], X[8 * s2 + 1]); w.y = pk_bf16(X[8 * s2 + 2], X[8 * s2 + 3]); w.z = pk_bf16(X[8 * s2 + 4], X[8 * s2 + 5]); w.w = pk_bf16(X[8 * s2 + 6], X[8 * s2 + 7]);
;       ls2 += (f32x2){X[8 * s2], X[8 * s2 + 1]}; ls2 += (f32x2){X[8 * s2 + 2], X[8 * s2 + 3]};
;       ls2 += (f32x2){X[8 * s2 + 4], X[8 * s2 + 5]}; ls2 += (f32x2){X[8 * s2 + 6], X[8 * s2 + 7]};
;       pf[s2] = __builtin_bit_cast(bf16x8, w);
;     }
; #pragma unroll
;     for (int s2 = 0; s2 < 2; ++s2)
; #pragma unroll
;       for (int dt = 0; dt < 4; ++dt) O[dt] = MFMA32(pf[s2], vf[s2][dt], O[dt]);
;     ...
;   for (int it = 0; it < npairs; ++it) {
;     const int set = it & 1;
;     if (it + 1 < npairs) { load_tile(2 * it + 2, rkA, rvA0, rvA1); load_tile(2 * it + 3, rkB, rvB0, rvB1); }
;     compute(2 * it, 2 * set);
;     compute(2 * it + 1, 2 * set + 1);
;     if (it + 1 < npairs) { store_tile(2 * (set ^ 1), rkA, rvA0, rvA1); store_tile(2 * (set ^ 1) + 1, rkB, rvB0, rvB1); }
;     __syncthreads();
	ds_write_b128 v192, v[124:127] offset:4608
	global_load_dwordx4 v[120:123], v[224:225], off
	s_mov_b32 s7, s51
	s_lshl_b64 s[10:11], s[6:7], 12
	v_lshl_add_u64 v[220:221], v[172:173], 0, s[10:11]
	v_add_f32_e32 v186, v186, v76
	v_add_f32_e32 v187, v187, v77
	v_add_f32_e32 v186, v186, v246
	v_add_f32_e32 v187, v187, v247
	s_waitcnt lgkmcnt(7)
	v_mfma_f32_32x32x16_bf16 v[48:63], v[240:243], v[148:151], v[48:63]
	v_add3_u32 v192, s8, v189, v190
	s_waitcnt vmcnt(4)
	ds_write_b128 v192, v[128:131] offset:18432
	global_load_dwordx4 v[124:127], v[220:221], off
	s_lshl_b64 s[10:11], s[6:7], 13
	v_lshl_add_u64 v[222:223], v[170:171], 0, s[10:11]
	v_add_f32_e32 v246, v82, v86
	v_add_f32_e32 v247, v83, v87
	v_add_f32_e32 v186, v186, v80
	v_add_f32_e32 v187, v187, v81
	s_waitcnt lgkmcnt(7)
	v_mfma_f32_32x32x16_bf16 v[32:47], v[240:243], v[144:147], v[32:47]
	s_waitcnt vmcnt(4)
	ds_write_b128 v192, v[132:135] offset:23552
	global_load_dwordx4 v[128:131], v[222:223], off
	v_lshl_add_u64 v[224:225], v[222:223], 0, s[20:21]
	v_add_f32_e32 v246, v246, v90
	v_add_f32_e32 v247, v247, v91
	v_add_f32_e32 v186, v186, v84
	v_add_f32_e32 v187, v187, v85
	s_waitcnt lgkmcnt(7)
	v_mfma_f32_32x32x16_bf16 v[16:31], v[240:243], v[136:139], v[16:31]
	global_load_dwordx4 v[132:135], v[224:225], off
	v_add_f32_e32 v246, v246, v94
	v_add_f32_e32 v247, v247, v95
	v_add_f32_e32 v186, v186, v88
	v_add_f32_e32 v187, v187, v89
	s_waitcnt lgkmcnt(6)
	v_mfma_f32_32x32x16_bf16 v[0:15], v[240:243], v[140:143], v[0:15]
	v_add_f32_e32 v186, v186, v92
	v_add_f32_e32 v187, v187, v93
	v_add_f32_e32 v186, v186, v246
	v_add_f32_e32 v187, v187, v247
	s_mov_b64 s[8:9], -1
	s_branch .Lat2_nopf
.Lat2_pvw:
	s_xor_b32 s7, s16, 2
	s_mul_i32 s8, s7, 0x2800
	s_add_i32 s8, s8, 32
	s_mulk_i32 s7, 0x1200
	v_add_u32_e32 v192, s7, v169
	v_add3_u32 v244, s8, v189, v190
	s_addk_i32 s8, 0x2800
	s_waitcnt lgkmcnt(7)
	v_mfma_f32_32x32x16_bf16 v[48:63], v[236:239], v[156:159], v[48:63]
	s_waitcnt vmcnt(5)
	ds_write_b128 v192, v[96:99]
	v_add_f32_e32 v246, v66, v70
	v_add_f32_e32 v247, v67, v71
	v_add_f32_e32 v186, v186, v64
	v_add_f32_e32 v187, v187, v65
	s_waitcnt lgkmcnt(7)
	v_mfma_f32_32x32x16_bf16 v[32:47], v[236:239], v[160:163], v[32:47]
	s_waitcnt vmcnt(4)
	ds_write_b128 v244, v[100:103] offset:18432
	v_add_f32_e32 v246, v246, v74
	v_add_f32_e32 v247, v247, v75
	v_add_f32_e32 v186, v186, v68
	v_add_f32_e32 v187, v187, v69
	s_waitcnt lgkmcnt(7)
	v_mfma_f32_32x32x16_bf16 v[16:31], v[236:239], v[164:167], v[16:31]
	s_waitcnt vmcnt(3)
	ds_write_b128 v244, v[120:123] offset:23552
	v_add_f32_e32 v246, v246, v78
	v_add_f32_e32 v247, v247, v79
	v_add_f32_e32 v186, v186, v72
	v_add_f32_e32 v187, v187, v73
	s_waitcnt lgkmcnt(7)
	v_mfma_f32_32x32x16_bf16 v[0:15], v[236:239], v[152:155], v[0:15]
	s_waitcnt vmcnt(2)
	ds_write_b128 v192, v[124:127] offset:4608
	v_add_f32_e32 v186, v186, v76
	v_add_f32_e32 v187, v187, v77
	v_add_f32_e32 v186, v186, v246
	v_add_f32_e32 v187, v187, v247
	s_waitcnt lgkmcnt(7)
	v_mfma_f32_32x32x16_bf16 v[48:63], v[240:243], v[148:151], v[48:63]
	v_add3_u32 v192, s8, v189, v190
	s_waitcnt vmcnt(1)
	ds_write_b128 v192, v[128:131] offset:18432
	v_add_f32_e32 v246, v82, v86
	v_add_f32_e32 v247, v83, v87
	v_add_f32_e32 v186, v186, v80
	v_add_f32_e32 v187, v187, v81
	s_waitcnt lgkmcnt(7)
	v_mfma_f32_32x32x16_bf16 v[32:47], v[240:243], v[144:147], v[32:47]
	s_waitcnt vmcnt(0)
	ds_write_b128 v192, v[132:135] offset:23552
	v_add_f32_e32 v246, v246, v90
	v_add_f32_e32 v247, v247, v91
	v_add_f32_e32 v186, v186, v84
	v_add_f32_e32 v187, v187, v85
	s_waitcnt lgkmcnt(7)
	v_mfma_f32_32x32x16_bf16 v[16:31], v[240:243], v[136:139], v[16:31]
	v_add_f32_e32 v246, v246, v94
	v_add_f32_e32 v247, v247, v95
	v_add_f32_e32 v186, v186, v88
	v_add_f32_e32 v187, v187, v89
	s_waitcnt lgkmcnt(6)
	v_mfma_f32_32x32x16_bf16 v[0:15], v[240:243], v[140:143], v[0:15]
	v_add_f32_e32 v186, v186, v92
	v_add_f32_e32 v187, v187, v93
	v_add_f32_e32 v186, v186, v246
	v_add_f32_e32 v187, v187, v247
	s_branch .Lat2_bot
.Lat2_pvplain:
	s_waitcnt lgkmcnt(7)
	v_mfma_f32_32x32x16_bf16 v[48:63], v[236:239], v[156:159], v[48:63]
	v_add_f32_e32 v246, v66, v70
	v_add_f32_e32 v247, v67, v71
	v_add_f32_e32 v186, v186, v64
	v_add_f32_e32 v187, v187, v65
	s_waitcnt lgkmcnt(6)
	v_mfma_f32_32x32x16_bf16 v[32:47], v[236:239], v[160:163], v[32:47]
	v_add_f32_e32 v246, v246, v74
	v_add_f32_e32 v247, v247, v75
	v_add_f32_e32 v186, v186, v68
	v_add_f32_e32 v187, v187, v69
	s_waitcnt lgkmcnt(5)
	v_mfma_f32_32x32x16_bf16 v[16:31], v[236:239], v[164:167], v[16:31]
	v_add_f32_e32 v246, v246, v78
	v_add_f32_e32 v247, v247, v79
	v_add_f32_e32 v186, v186, v72
	v_add_f32_e32 v187, v187, v73
	s_waitcnt lgkmcnt(4)
	v_mfma_f32_32x32x16_bf16 v[0:15], v[236:239], v[152:155], v[0:15]
	v_add_f32_e32 v186, v186, v76
	v_add_f32_e32 v187, v187, v77
	v_add_f32_e32 v186, v186, v246
	v_add_f32_e32 v187, v187, v247
	s_waitcnt lgkmcnt(3)
	v_mfma_f32_32x32x16_bf16 v[48:63], v[240:243], v[148:151], v[48:63]
	v_add_f32_e32 v246, v82, v86
	v_add_f32_e32 v247, v83, v87
	v_add_f32_e32 v186, v186, v80
	v_add_f32_e32 v187, v187, v81
	s_waitcnt lgkmcnt(2)
	v_mfma_f32_32x32x16_bf16 v[32:47], v[240:243], v[144:147], v[32:47]
	v_add_f32_e32 v246, v246, v90
	v_add_f32_e32 v247, v247, v91
	v_add_f32_e32 v186, v186, v84
	v_add_f32_e32 v187, v187, v85
	s_waitcnt lgkmcnt(1)
	v_mfma_f32_32x32x16_bf16 v[16:31], v[240:243], v[136:139], v[16:31]
	v_add_f32_e32 v246, v246, v94
	v_add_f32_e32 v247, v247, v95
	v_add_f32_e32 v186, v186, v88
	v_add_f32_e32 v187, v187, v89
	s_waitcnt lgkmcnt(0)
	v_mfma_f32_32x32x16_bf16 v[0:15], v[240:243], v[140:143], v[0:15]
	v_add_f32_e32 v186, v186, v92
	v_add_f32_e32 v187, v187, v93
	v_add_f32_e32 v186, v186, v246
	v_add_f32_e32 v187, v187, v247
